# last layer down-proj epilogue: 16 residual loads in flight, token rows stored straight to output
# speedup vs baseline: 1.0176x; 1.0050x over previous
; __device__ __forceinline__ unsigned cvt_pk_bf16(float lo, float hi) { unsigned r; asm volatile("v_cvt_pk_bf16_f32 %0, %1, %2" : "=v"(r) : "v"(lo), "v"(hi)); return r; }
;     __device__ __forceinline__ void operator()(const f32x4 (&acc)[2][2][4][2], const Unit& u, int wr, int wc, int fr, int fq) const {
;     ...
;         for (int ai = 0; ai < 2; ++ai)
; #pragma unroll
;             for (int m = 0; m < 4; ++m) { const int row = u.pm * BM + ai * HALF + wr * 64 + m * 16 + fr; const int b = row >= 4224 ? 1 : 0, t = row - b * 4224; float ss = 0.f;
; #pragma unroll
;                 for (int bj = 0; bj < 2; ++bj)
; #pragma unroll
;                     for (int n = 0; n < 2; ++n) { const int col = u.pn * BM + bj * HALF + wc * 32 + n * 16 + 4 * fq; float* p = H + (size_t)row * 2048 + col;
;                         const f32x4 v = *(const f32x4*)p + acc[ai][bj][m][n] * s; *(f32x4*)p = v;
;                         if (SSQ != nullptr) { typedef unsigned u32x2 __attribute__((ext_vector_type(2))); u32x2 w; w.x = cvt_pk_bf16(v[0], v[1]); w.y = cvt_pk_bf16(v[2], v[3]); *(u32x2*)(HB + (size_t)row * 2048 + col) = w;
;                             ss += (v[0] * v[0] + v[1] * v[1]) + (v[2] * v[2] + v[3] * v[3]); }
;                         if (OUT != 0ull && t >= 128) *(__attribute__((address_space(1))) f32x4*)(OUT + ((size_t)(b * 4096 + t - 128) * 2048 + col) * 4) = v; }
.Lnepi_slow:
	s_and_b64 vcc, exec, s[16:17]
	s_cbranch_vccnz .Lnepi_slow2
	s_and_b64 vcc, exec, s[30:31]
	s_cbranch_vccz .Lnepi_slow2
	v_mov_b32_e32 v143, 0
	v_lshlrev_b32_e32 v159, 13, v144
	v_lshl_add_u32 v159, v142, 2, v159
	v_lshl_add_u64 v[160:161], v[142:143], 2, s[18:19]
	v_lshl_add_u64 v[166:167], v[142:143], 2, s[14:15]
	global_load_dwordx4 v[182:185], v159, s[14:15]
	global_load_dwordx4 v[186:189], v159, s[14:15] offset:64
	global_load_dwordx4 v[190:193], v159, s[14:15] offset:512
	global_load_dwordx4 v[194:197], v159, s[14:15] offset:576
	v_add_u32_e32 v244, 0x20000, v159
	global_load_dwordx4 v[198:201], v244, s[14:15]
	global_load_dwordx4 v[202:205], v244, s[14:15] offset:64
	global_load_dwordx4 v[206:209], v244, s[14:15] offset:512
	global_load_dwordx4 v[210:213], v244, s[14:15] offset:576
	v_add_u32_e32 v244, 0x40000, v159
	global_load_dwordx4 v[214:217], v244, s[14:15]
	global_load_dwordx4 v[218:221], v244, s[14:15] offset:64
	global_load_dwordx4 v[222:225], v244, s[14:15] offset:512
	global_load_dwordx4 v[226:229], v244, s[14:15] offset:576
	v_add_u32_e32 v244, 0x60000, v159
	global_load_dwordx4 v[146:149], v244, s[14:15]
	global_load_dwordx4 v[150:153], v244, s[14:15] offset:64
	global_load_dwordx4 v[154:157], v244, s[14:15] offset:512
	global_load_dwordx4 v[130:133], v244, s[14:15] offset:576
	v_cmp_lt_i32_e32 vcc, s89, v144
	s_nop 1
	v_cndmask_b32_e32 v0, 0, v237, vcc
	v_add_u32_e32 v0, v0, v144
	v_cndmask_b32_e32 v244, v238, v239, vcc
	v_cmp_lt_i32_e64 s[6:7], s69, v0
	v_add_u32_e32 v0, v0, v244
	v_lshlrev_b64 v[168:169], 13, v[0:1]
	v_mov_b32_e32 v0, v144
	v_lshl_add_u64 v[168:169], v[168:169], 0, v[160:161]
	v_lshlrev_b64 v[240:241], 13, v[0:1]
	v_lshl_add_u64 v[240:241], v[240:241], 0, v[166:167]
	v_cndmask_b32_e64 v242, v240, v168, s[6:7]
	v_cndmask_b32_e64 v243, v241, v169, s[6:7]
	s_waitcnt vmcnt(12)
	v_pk_fma_f32 v[128:129], v[128:129], 0.5, v[184:185] op_sel_hi:[1,0,1]
	v_pk_fma_f32 v[126:127], v[126:127], 0.5, v[182:183] op_sel_hi:[1,0,1]
	global_store_dwordx4 v[242:243], v[126:129], off
	v_pk_fma_f32 v[124:125], v[124:125], 0.5, v[188:189] op_sel_hi:[1,0,1]
	v_pk_fma_f32 v[122:123], v[122:123], 0.5, v[186:187] op_sel_hi:[1,0,1]
	global_store_dwordx4 v[242:243], v[122:125], off offset:64
	v_pk_fma_f32 v[96:97], v[96:97], 0.5, v[192:193] op_sel_hi:[1,0,1]
	v_pk_fma_f32 v[94:95], v[94:95], 0.5, v[190:191] op_sel_hi:[1,0,1]
	global_store_dwordx4 v[242:243], v[94:97], off offset:512
	v_pk_fma_f32 v[92:93], v[92:93], 0.5, v[196:197] op_sel_hi:[1,0,1]
	v_pk_fma_f32 v[90:91], v[90:91], 0.5, v[194:195] op_sel_hi:[1,0,1]
	global_store_dwordx4 v[242:243], v[90:93], off offset:576
	v_add_u32_e32 v244, 0x100000, v159
	global_load_dwordx4 v[182:185], v244, s[14:15]
	global_load_dwordx4 v[186:189], v244, s[14:15] offset:64
	global_load_dwordx4 v[190:193], v244, s[14:15] offset:512
	global_load_dwordx4 v[194:197], v244, s[14:15] offset:576
	v_add_u32_e32 v245, 16, v144
	v_cmp_lt_i32_e32 vcc, s89, v245
	s_nop 1
	v_cndmask_b32_e32 v0, 0, v237, vcc
	v_add_u32_e32 v0, v0, v245
	v_cndmask_b32_e32 v244, v238, v239, vcc
	v_cmp_lt_i32_e64 s[6:7], s69, v0
	v_add_u32_e32 v0, v0, v244
	v_lshlrev_b64 v[168:169], 13, v[0:1]
	v_mov_b32_e32 v0, v245
	v_lshl_add_u64 v[168:169], v[168:169], 0, v[160:161]
	v_lshlrev_b64 v[240:241], 13, v[0:1]
	v_lshl_add_u64 v[240:241], v[240:241], 0, v[166:167]
	v_cndmask_b32_e64 v242, v240, v168, s[6:7]
	v_cndmask_b32_e64 v243, v241, v169, s[6:7]
	s_waitcnt vmcnt(16)
	v_pk_fma_f32 v[120:121], v[120:121], 0.5, v[200:201] op_sel_hi:[1,0,1]
	v_pk_fma_f32 v[118:119], v[118:119], 0.5, v[198:199] op_sel_hi:[1,0,1]
	global_store_dwordx4 v[242:243], v[118:121], off
	v_pk_fma_f32 v[116:117], v[116:117], 0.5, v[204:205] op_sel_hi:[1,0,1]
	v_pk_fma_f32 v[114:115], v[114:115], 0.5, v[202:203] op_sel_hi:[1,0,1]
	global_store_dwordx4 v[242:243], v[114:117], off offset:64
	v_pk_fma_f32 v[88:89], v[88:89], 0.5, v[208:209] op_sel_hi:[1,0,1]
	v_pk_fma_f32 v[86:87], v[86:87], 0.5, v[206:207] op_sel_hi:[1,0,1]
	global_store_dwordx4 v[242:243], v[86:89], off offset:512
	v_pk_fma_f32 v[84:85], v[84:85], 0.5, v[212:213] op_sel_hi:[1,0,1]
	v_pk_fma_f32 v[82:83], v[82:83], 0.5, v[210:211] op_sel_hi:[1,0,1]
	global_store_dwordx4 v[242:243], v[82:85], off offset:576
	v_add_u32_e32 v244, 0x120000, v159
	global_load_dwordx4 v[198:201], v244, s[14:15]
	global_load_dwordx4 v[202:205], v244, s[14:15] offset:64
	global_load_dwordx4 v[206:209], v244, s[14:15] offset:512
	global_load_dwordx4 v[210:213], v244, s[14:15] offset:576
	v_add_u32_e32 v245, 32, v144
	v_cmp_lt_i32_e32 vcc, s89, v245
	s_nop 1
	v_cndmask_b32_e32 v0, 0, v237, vcc
	v_add_u32_e32 v0, v0, v245
	v_cndmask_b32_e32 v244, v238, v239, vcc
	v_cmp_lt_i32_e64 s[6:7], s69, v0
	v_add_u32_e32 v0, v0, v244
	v_lshlrev_b64 v[168:169], 13, v[0:1]
	v_mov_b32_e32 v0, v245
	v_lshl_add_u64 v[168:169], v[168:169], 0, v[160:161]
	v_lshlrev_b64 v[240:241], 13, v[0:1]
	v_lshl_add_u64 v[240:241], v[240:241], 0, v[166:167]
	v_cndmask_b32_e64 v242, v240, v168, s[6:7]
	v_cndmask_b32_e64 v243, v241, v169, s[6:7]
	s_waitcnt vmcnt(20)
; __device__ __forceinline__ unsigned cvt_pk_bf16(float lo, float hi) { unsigned r; asm volatile("v_cvt_pk_bf16_f32 %0, %1, %2" : "=v"(r) : "v"(lo), "v"(hi)); return r; }
;     __device__ __forceinline__ void operator()(const f32x4 (&acc)[2][2][4][2], const Unit& u, int wr, int wc, int fr, int fq) const {
;     ...
;         for (int ai = 0; ai < 2; ++ai)
; #pragma unroll
;             for (int m = 0; m < 4; ++m) { const int row = u.pm * BM + ai * HALF + wr * 64 + m * 16 + fr; const int b = row >= 4224 ? 1 : 0, t = row - b * 4224; float ss = 0.f;
; #pragma unroll
;                 for (int bj = 0; bj < 2; ++bj)
; #pragma unroll
;                     for (int n = 0; n < 2; ++n) { const int col = u.pn * BM + bj * HALF + wc * 32 + n * 16 + 4 * fq; float* p = H + (size_t)row * 2048 + col;
;                         const f32x4 v = *(const f32x4*)p + acc[ai][bj][m][n] * s; *(f32x4*)p = v;
;                         if (SSQ != nullptr) { typedef unsigned u32x2 __attribute__((ext_vector_type(2))); u32x2 w; w.x = cvt_pk_bf16(v[0], v[1]); w.y = cvt_pk_bf16(v[2], v[3]); *(u32x2*)(HB + (size_t)row * 2048 + col) = w;
;                             ss += (v[0] * v[0] + v[1] * v[1]) + (v[2] * v[2] + v[3] * v[3]); }
;                         if (OUT != 0ull && t >= 128) *(__attribute__((address_space(1))) f32x4*)(OUT + ((size_t)(b * 4096 + t - 128) * 2048 + col) * 4) = v; }
	v_pk_fma_f32 v[112:113], v[112:113], 0.5, v[216:217] op_sel_hi:[1,0,1]
	v_pk_fma_f32 v[110:111], v[110:111], 0.5, v[214:215] op_sel_hi:[1,0,1]
	global_store_dwordx4 v[242:243], v[110:113], off
	v_pk_fma_f32 v[108:109], v[108:109], 0.5, v[220:221] op_sel_hi:[1,0,1]
	v_pk_fma_f32 v[106:107], v[106:107], 0.5, v[218:219] op_sel_hi:[1,0,1]
	global_store_dwordx4 v[242:243], v[106:109], off offset:64
	v_pk_fma_f32 v[80:81], v[80:81], 0.5, v[224:225] op_sel_hi:[1,0,1]
	v_pk_fma_f32 v[78:79], v[78:79], 0.5, v[222:223] op_sel_hi:[1,0,1]
	global_store_dwordx4 v[242:243], v[78:81], off offset:512
	v_pk_fma_f32 v[76:77], v[76:77], 0.5, v[228:229] op_sel_hi:[1,0,1]
	v_pk_fma_f32 v[74:75], v[74:75], 0.5, v[226:227] op_sel_hi:[1,0,1]
	global_store_dwordx4 v[242:243], v[74:77], off offset:576
	v_add_u32_e32 v244, 0x140000, v159
	global_load_dwordx4 v[214:217], v244, s[14:15]
	global_load_dwordx4 v[218:221], v244, s[14:15] offset:64
	global_load_dwordx4 v[222:225], v244, s[14:15] offset:512
	global_load_dwordx4 v[226:229], v244, s[14:15] offset:576
	v_add_u32_e32 v245, 48, v144
	v_cmp_lt_i32_e32 vcc, s89, v245
	s_nop 1
	v_cndmask_b32_e32 v0, 0, v237, vcc
	v_add_u32_e32 v0, v0, v245
	v_cndmask_b32_e32 v244, v238, v239, vcc
	v_cmp_lt_i32_e64 s[6:7], s69, v0
	v_add_u32_e32 v0, v0, v244
	v_lshlrev_b64 v[168:169], 13, v[0:1]
	v_mov_b32_e32 v0, v245
	v_lshl_add_u64 v[168:169], v[168:169], 0, v[160:161]
	v_lshlrev_b64 v[240:241], 13, v[0:1]
	v_lshl_add_u64 v[240:241], v[240:241], 0, v[166:167]
	v_cndmask_b32_e64 v242, v240, v168, s[6:7]
	v_cndmask_b32_e64 v243, v241, v169, s[6:7]
	s_waitcnt vmcnt(24)
	v_pk_fma_f32 v[104:105], v[104:105], 0.5, v[148:149] op_sel_hi:[1,0,1]
	v_pk_fma_f32 v[102:103], v[102:103], 0.5, v[146:147] op_sel_hi:[1,0,1]
	global_store_dwordx4 v[242:243], v[102:105], off
	v_pk_fma_f32 v[100:101], v[100:101], 0.5, v[152:153] op_sel_hi:[1,0,1]
	v_pk_fma_f32 v[98:99], v[98:99], 0.5, v[150:151] op_sel_hi:[1,0,1]
	global_store_dwordx4 v[242:243], v[98:101], off offset:64
	v_pk_fma_f32 v[72:73], v[72:73], 0.5, v[156:157] op_sel_hi:[1,0,1]
	v_pk_fma_f32 v[70:71], v[70:71], 0.5, v[154:155] op_sel_hi:[1,0,1]
	global_store_dwordx4 v[242:243], v[70:73], off offset:512
	v_pk_fma_f32 v[68:69], v[68:69], 0.5, v[132:133] op_sel_hi:[1,0,1]
	v_pk_fma_f32 v[66:67], v[66:67], 0.5, v[130:131] op_sel_hi:[1,0,1]
	global_store_dwordx4 v[242:243], v[66:69], off offset:576
	v_add_u32_e32 v244, 0x160000, v159
	global_load_dwordx4 v[146:149], v244, s[14:15]
	global_load_dwordx4 v[150:153], v244, s[14:15] offset:64
	global_load_dwordx4 v[154:157], v244, s[14:15] offset:512
	global_load_dwordx4 v[130:133], v244, s[14:15] offset:576
	v_add_u32_e32 v245, 128, v144
	v_cmp_lt_i32_e32 vcc, s89, v245
	s_nop 1
	v_cndmask_b32_e32 v0, 0, v237, vcc
	v_add_u32_e32 v0, v0, v245
	v_cndmask_b32_e32 v244, v238, v239, vcc
	v_cmp_lt_i32_e64 s[6:7], s69, v0
	v_add_u32_e32 v0, v0, v244
	v_lshlrev_b64 v[168:169], 13, v[0:1]
	v_mov_b32_e32 v0, v245
	v_lshl_add_u64 v[168:169], v[168:169], 0, v[160:161]
	v_lshlrev_b64 v[240:241], 13, v[0:1]
	v_lshl_add_u64 v[240:241], v[240:241], 0, v[166:167]
	v_cndmask_b32_e64 v242, v240, v168, s[6:7]
	v_cndmask_b32_e64 v243, v241, v169, s[6:7]
	s_waitcnt vmcnt(24)
	v_pk_fma_f32 v[64:65], v[64:65], 0.5, v[184:185] op_sel_hi:[1,0,1]
	v_pk_fma_f32 v[62:63], v[62:63], 0.5, v[182:183] op_sel_hi:[1,0,1]
	global_store_dwordx4 v[242:243], v[62:65], off
	v_pk_fma_f32 v[60:61], v[60:61], 0.5, v[188:189] op_sel_hi:[1,0,1]
	v_pk_fma_f32 v[58:59], v[58:59], 0.5, v[186:187] op_sel_hi:[1,0,1]
	global_store_dwordx4 v[242:243], v[58:61], off offset:64
	v_pk_fma_f32 v[32:33], v[32:33], 0.5, v[192:193] op_sel_hi:[1,0,1]
	v_pk_fma_f32 v[30:31], v[30:31], 0.5, v[190:191] op_sel_hi:[1,0,1]
	global_store_dwordx4 v[242:243], v[30:33], off offset:512
	v_pk_fma_f32 v[28:29], v[28:29], 0.5, v[196:197] op_sel_hi:[1,0,1]
	v_pk_fma_f32 v[26:27], v[26:27], 0.5, v[194:195] op_sel_hi:[1,0,1]
	global_store_dwordx4 v[242:243], v[26:29], off offset:576
	v_add_u32_e32 v245, 144, v144
	v_cmp_lt_i32_e32 vcc, s89, v245
	s_nop 1
	v_cndmask_b32_e32 v0, 0, v237, vcc
	v_add_u32_e32 v0, v0, v245
	v_cndmask_b32_e32 v244, v238, v239, vcc
	v_cmp_lt_i32_e64 s[6:7], s69, v0
	v_add_u32_e32 v0, v0, v244
	v_lshlrev_b64 v[168:169], 13, v[0:1]
	v_mov_b32_e32 v0, v245
	v_lshl_add_u64 v[168:169], v[168:169], 0, v[160:161]
	v_lshlrev_b64 v[240:241], 13, v[0:1]
	v_lshl_add_u64 v[240:241], v[240:241], 0, v[166:167]
	v_cndmask_b32_e64 v242, v240, v168, s[6:7]
	v_cndmask_b32_e64 v243, v241, v169, s[6:7]
	s_waitcnt vmcnt(20)
; __device__ __forceinline__ unsigned cvt_pk_bf16(float lo, float hi) { unsigned r; asm volatile("v_cvt_pk_bf16_f32 %0, %1, %2" : "=v"(r) : "v"(lo), "v"(hi)); return r; }
;     __device__ __forceinline__ void operator()(const f32x4 (&acc)[2][2][4][2], const Unit& u, int wr, int wc, int fr, int fq) const {
;     ...
;         for (int ai = 0; ai < 2; ++ai)
; #pragma unroll
;             for (int m = 0; m < 4; ++m) { const int row = u.pm * BM + ai * HALF + wr * 64 + m * 16 + fr; const int b = row >= 4224 ? 1 : 0, t = row - b * 4224; float ss = 0.f;
; #pragma unroll
;                 for (int bj = 0; bj < 2; ++bj)
; #pragma unroll
;                     for (int n = 0; n < 2; ++n) { const int col = u.pn * BM + bj * HALF + wc * 32 + n * 16 + 4 * fq; float* p = H + (size_t)row * 2048 + col;
;                         const f32x4 v = *(const f32x4*)p + acc[ai][bj][m][n] * s; *(f32x4*)p = v;
;                         if (SSQ != nullptr) { typedef unsigned u32x2 __attribute__((ext_vector_type(2))); u32x2 w; w.x = cvt_pk_bf16(v[0], v[1]); w.y = cvt_pk_bf16(v[2], v[3]); *(u32x2*)(HB + (size_t)row * 2048 + col) = w;
;                             ss += (v[0] * v[0] + v[1] * v[1]) + (v[2] * v[2] + v[3] * v[3]); }
;                         if (OUT != 0ull && t >= 128) *(__attribute__((address_space(1))) f32x4*)(OUT + ((size_t)(b * 4096 + t - 128) * 2048 + col) * 4) = v; }
	v_pk_fma_f32 v[56:57], v[56:57], 0.5, v[200:201] op_sel_hi:[1,0,1]
	v_pk_fma_f32 v[54:55], v[54:55], 0.5, v[198:199] op_sel_hi:[1,0,1]
	global_store_dwordx4 v[242:243], v[54:57], off
	v_pk_fma_f32 v[52:53], v[52:53], 0.5, v[204:205] op_sel_hi:[1,0,1]
	v_pk_fma_f32 v[50:51], v[50:51], 0.5, v[202:203] op_sel_hi:[1,0,1]
	global_store_dwordx4 v[242:243], v[50:53], off offset:64
	v_pk_fma_f32 v[24:25], v[24:25], 0.5, v[208:209] op_sel_hi:[1,0,1]
	v_pk_fma_f32 v[22:23], v[22:23], 0.5, v[206:207] op_sel_hi:[1,0,1]
	global_store_dwordx4 v[242:243], v[22:25], off offset:512
	v_pk_fma_f32 v[20:21], v[20:21], 0.5, v[212:213] op_sel_hi:[1,0,1]
	v_pk_fma_f32 v[18:19], v[18:19], 0.5, v[210:211] op_sel_hi:[1,0,1]
	global_store_dwordx4 v[242:243], v[18:21], off offset:576
	v_add_u32_e32 v245, 160, v144
	v_cmp_lt_i32_e32 vcc, s89, v245
	s_nop 1
	v_cndmask_b32_e32 v0, 0, v237, vcc
	v_add_u32_e32 v0, v0, v245
	v_cndmask_b32_e32 v244, v238, v239, vcc
	v_cmp_lt_i32_e64 s[6:7], s69, v0
	v_add_u32_e32 v0, v0, v244
	v_lshlrev_b64 v[168:169], 13, v[0:1]
	v_mov_b32_e32 v0, v245
	v_lshl_add_u64 v[168:169], v[168:169], 0, v[160:161]
	v_lshlrev_b64 v[240:241], 13, v[0:1]
	v_lshl_add_u64 v[240:241], v[240:241], 0, v[166:167]
	v_cndmask_b32_e64 v242, v240, v168, s[6:7]
	v_cndmask_b32_e64 v243, v241, v169, s[6:7]
	s_waitcnt vmcnt(16)
	v_pk_fma_f32 v[48:49], v[48:49], 0.5, v[216:217] op_sel_hi:[1,0,1]
	v_pk_fma_f32 v[46:47], v[46:47], 0.5, v[214:215] op_sel_hi:[1,0,1]
	global_store_dwordx4 v[242:243], v[46:49], off
	v_pk_fma_f32 v[44:45], v[44:45], 0.5, v[220:221] op_sel_hi:[1,0,1]
	v_pk_fma_f32 v[42:43], v[42:43], 0.5, v[218:219] op_sel_hi:[1,0,1]
	global_store_dwordx4 v[242:243], v[42:45], off offset:64
	v_pk_fma_f32 v[16:17], v[16:17], 0.5, v[224:225] op_sel_hi:[1,0,1]
	v_pk_fma_f32 v[14:15], v[14:15], 0.5, v[222:223] op_sel_hi:[1,0,1]
	global_store_dwordx4 v[242:243], v[14:17], off offset:512
	v_pk_fma_f32 v[12:13], v[12:13], 0.5, v[228:229] op_sel_hi:[1,0,1]
	v_pk_fma_f32 v[10:11], v[10:11], 0.5, v[226:227] op_sel_hi:[1,0,1]
	global_store_dwordx4 v[242:243], v[10:13], off offset:576
	v_add_u32_e32 v245, 176, v144
	v_cmp_lt_i32_e32 vcc, s89, v245
	s_nop 1
	v_cndmask_b32_e32 v0, 0, v237, vcc
	v_add_u32_e32 v0, v0, v245
	v_cndmask_b32_e32 v244, v238, v239, vcc
	v_cmp_lt_i32_e64 s[6:7], s69, v0
	v_add_u32_e32 v0, v0, v244
	v_lshlrev_b64 v[168:169], 13, v[0:1]
	v_mov_b32_e32 v0, v245
	v_lshl_add_u64 v[168:169], v[168:169], 0, v[160:161]
	v_lshlrev_b64 v[240:241], 13, v[0:1]
	v_lshl_add_u64 v[240:241], v[240:241], 0, v[166:167]
	v_cndmask_b32_e64 v242, v240, v168, s[6:7]
	v_cndmask_b32_e64 v243, v241, v169, s[6:7]
	s_waitcnt vmcnt(12)
	v_pk_fma_f32 v[40:41], v[40:41], 0.5, v[148:149] op_sel_hi:[1,0,1]
	v_pk_fma_f32 v[38:39], v[38:39], 0.5, v[146:147] op_sel_hi:[1,0,1]
	global_store_dwordx4 v[242:243], v[38:41], off
	v_pk_fma_f32 v[36:37], v[36:37], 0.5, v[152:153] op_sel_hi:[1,0,1]
	v_pk_fma_f32 v[34:35], v[34:35], 0.5, v[150:151] op_sel_hi:[1,0,1]
	global_store_dwordx4 v[242:243], v[34:37], off offset:64
	v_pk_fma_f32 v[8:9], v[8:9], 0.5, v[156:157] op_sel_hi:[1,0,1]
	v_pk_fma_f32 v[6:7], v[6:7], 0.5, v[154:155] op_sel_hi:[1,0,1]
	global_store_dwordx4 v[242:243], v[6:9], off offset:512
	v_pk_fma_f32 v[4:5], v[4:5], 0.5, v[132:133] op_sel_hi:[1,0,1]
	v_pk_fma_f32 v[2:3], v[2:3], 0.5, v[130:131] op_sel_hi:[1,0,1]
	global_store_dwordx4 v[242:243], v[2:5], off offset:576
	s_branch .LBB0_1744
